# v14 + M1 fp8 merge-gate epilogue regenerated: packed mul/add/fma per 8 codes, same f32 ops and byte packing
# baseline (speedup 1.0000x reference)
;     __device__ __forceinline__ void operator()(const f32x4 (&acc)[2][2][4][2], const Unit& u, int wr, int wc, int fr, int fq) const {
;     ...
;                 for (int bj = 0; bj < 2; ++bj) { const f32x4 v0 = acc[ai][bj][m][0] * sc, v1 = acc[ai][bj][m][1] * sc; unsigned q[8];
; #pragma unroll
;                     for (int j = 0; j < 4; ++j) { const float s0 = 255.0f * __builtin_amdgcn_rcpf(1.0f + __builtin_amdgcn_exp2f(-1.44269504089f * __builtin_amdgcn_fmed3f(v0[j], -30.f, 30.f))) + 0.5f,
;                                                               s1 = 255.0f * __builtin_amdgcn_rcpf(1.0f + __builtin_amdgcn_exp2f(-1.44269504089f * __builtin_amdgcn_fmed3f(v1[j], -30.f, 30.f))) + 0.5f;
;                         q[j] = (unsigned)__builtin_amdgcn_fmed3f(s0, 1.0f, 255.0f); q[4 + j] = (unsigned)__builtin_amdgcn_fmed3f(s1, 1.0f, 255.0f); }
;                     u32x2 w; w.x = q[0] | (q[1] << 8) | (q[2] << 16) | (q[3] << 24); w.y = q[4] | (q[5] << 8) | (q[6] << 16) | (q[7] << 24);
;                     *(u32x2*)(Q + row * 6144 + u.pn * BM + colt + bj * HALF) = w; } }
.LBB0_1136:
	s_mov_b32 s98, 0xbfb8aa3b
	s_mov_b32 s99, 0xbfb8aa3b
	v_mov_b32_e32 v14, s2
	v_lshl_add_u32 v4, s48, 8, v207
	s_lshl_b32 s48, s49, 8
	v_mov_b64_e32 v[2:3], s[26:27]
	s_ashr_i32 s49, s48, 31
	v_mad_i64_i32 v[8:9], s[50:51], v4, s33, v[2:3]
	v_lshl_add_u64 v[8:9], v[8:9], 0, s[48:49]
	v_lshl_add_u64 v[8:9], v[8:9], 0, v[192:193]
	s_nop 15
	s_nop 15
	v_pk_mul_f32 v[16:17], v[206:207], v[160:161] op_sel_hi:[0,1]
	v_pk_mul_f32 v[18:19], v[206:207], v[162:163] op_sel_hi:[0,1]
	v_pk_mul_f32 v[20:21], v[206:207], v[156:157] op_sel_hi:[0,1]
	v_pk_mul_f32 v[22:23], v[206:207], v[158:159] op_sel_hi:[0,1]
	v_med3_f32 v16, v16, s96, v231
	v_med3_f32 v17, v17, s96, v231
	v_med3_f32 v18, v18, s96, v231
	v_med3_f32 v19, v19, s96, v231
	v_med3_f32 v20, v20, s96, v231
	v_med3_f32 v21, v21, s96, v231
	v_med3_f32 v22, v22, s96, v231
	v_med3_f32 v23, v23, s96, v231
	v_pk_mul_f32 v[16:17], v[16:17], s[98:99]
	v_pk_mul_f32 v[18:19], v[18:19], s[98:99]
	v_pk_mul_f32 v[20:21], v[20:21], s[98:99]
	v_pk_mul_f32 v[22:23], v[22:23], s[98:99]
	v_exp_f32_e32 v16, v16
	v_exp_f32_e32 v17, v17
	v_exp_f32_e32 v18, v18
	v_exp_f32_e32 v19, v19
	v_exp_f32_e32 v20, v20
	v_exp_f32_e32 v21, v21
	v_exp_f32_e32 v22, v22
	v_exp_f32_e32 v23, v23
	v_pk_add_f32 v[16:17], v[16:17], 1.0 op_sel_hi:[1,0]
	v_pk_add_f32 v[18:19], v[18:19], 1.0 op_sel_hi:[1,0]
	v_pk_add_f32 v[20:21], v[20:21], 1.0 op_sel_hi:[1,0]
	v_pk_add_f32 v[22:23], v[22:23], 1.0 op_sel_hi:[1,0]
	v_rcp_f32_e32 v16, v16
	v_rcp_f32_e32 v17, v17
	v_rcp_f32_e32 v18, v18
	v_rcp_f32_e32 v19, v19
	v_rcp_f32_e32 v20, v20
	v_rcp_f32_e32 v21, v21
	v_rcp_f32_e32 v22, v22
	v_rcp_f32_e32 v23, v23
	v_pk_fma_f32 v[16:17], v[16:17], v[14:15], 0.5 op_sel_hi:[1,0,0]
	v_pk_fma_f32 v[18:19], v[18:19], v[14:15], 0.5 op_sel_hi:[1,0,0]
	v_pk_fma_f32 v[20:21], v[20:21], v[14:15], 0.5 op_sel_hi:[1,0,0]
	v_pk_fma_f32 v[22:23], v[22:23], v[14:15], 0.5 op_sel_hi:[1,0,0]
	v_med3_f32 v16, v16, 1.0, v232
	v_med3_f32 v17, v17, 1.0, v232
	v_med3_f32 v18, v18, 1.0, v232
	v_med3_f32 v19, v19, 1.0, v232
	v_med3_f32 v20, v20, 1.0, v232
	v_med3_f32 v21, v21, 1.0, v232
	v_med3_f32 v22, v22, 1.0, v232
	v_med3_f32 v23, v23, 1.0, v232
	v_cvt_u32_f32_e32 v16, v16
	v_cvt_u32_f32_e32 v17, v17
	v_cvt_u32_f32_sdwa v18, v18 dst_sel:WORD_1 dst_unused:UNUSED_PAD src0_sel:DWORD
	v_cvt_u32_f32_sdwa v19, v19 dst_sel:BYTE_3 dst_unused:UNUSED_PAD src0_sel:DWORD
	v_cvt_u32_f32_e32 v20, v20
	v_cvt_u32_f32_e32 v21, v21
	v_cvt_u32_f32_sdwa v22, v22 dst_sel:WORD_1 dst_unused:UNUSED_PAD src0_sel:DWORD
	v_cvt_u32_f32_sdwa v23, v23 dst_sel:BYTE_3 dst_unused:UNUSED_PAD src0_sel:DWORD
	v_lshl_or_b32 v16, v17, 8, v16
	v_lshl_or_b32 v20, v21, 8, v20
	v_or3_b32 v16, v16, v18, v19
	v_or3_b32 v17, v20, v22, v23
	global_store_dwordx2 v[8:9], v[16:17], off
	v_pk_mul_f32 v[24:25], v[206:207], v[152:153] op_sel_hi:[0,1]
	v_pk_mul_f32 v[26:27], v[206:207], v[154:155] op_sel_hi:[0,1]
	v_pk_mul_f32 v[28:29], v[206:207], v[148:149] op_sel_hi:[0,1]
	v_pk_mul_f32 v[30:31], v[206:207], v[150:151] op_sel_hi:[0,1]
	v_med3_f32 v24, v24, s96, v231
	v_med3_f32 v25, v25, s96, v231
	v_med3_f32 v26, v26, s96, v231
	v_med3_f32 v27, v27, s96, v231
	v_med3_f32 v28, v28, s96, v231
	v_med3_f32 v29, v29, s96, v231
	v_med3_f32 v30, v30, s96, v231
	v_med3_f32 v31, v31, s96, v231
	v_pk_mul_f32 v[24:25], v[24:25], s[98:99]
	v_pk_mul_f32 v[26:27], v[26:27], s[98:99]
	v_pk_mul_f32 v[28:29], v[28:29], s[98:99]
	v_pk_mul_f32 v[30:31], v[30:31], s[98:99]
	v_exp_f32_e32 v24, v24
	v_exp_f32_e32 v25, v25
	v_exp_f32_e32 v26, v26
	v_exp_f32_e32 v27, v27
	v_exp_f32_e32 v28, v28
	v_exp_f32_e32 v29, v29
	v_exp_f32_e32 v30, v30
	v_exp_f32_e32 v31, v31
	v_pk_add_f32 v[24:25], v[24:25], 1.0 op_sel_hi:[1,0]
	v_pk_add_f32 v[26:27], v[26:27], 1.0 op_sel_hi:[1,0]
	v_pk_add_f32 v[28:29], v[28:29], 1.0 op_sel_hi:[1,0]
	v_pk_add_f32 v[30:31], v[30:31], 1.0 op_sel_hi:[1,0]
	v_rcp_f32_e32 v24, v24
	v_rcp_f32_e32 v25, v25
	v_rcp_f32_e32 v26, v26
	v_rcp_f32_e32 v27, v27
	v_rcp_f32_e32 v28, v28
	v_rcp_f32_e32 v29, v29
	v_rcp_f32_e32 v30, v30
	v_rcp_f32_e32 v31, v31
	v_pk_fma_f32 v[24:25], v[24:25], v[14:15], 0.5 op_sel_hi:[1,0,0]
	v_pk_fma_f32 v[26:27], v[26:27], v[14:15], 0.5 op_sel_hi:[1,0,0]
	v_pk_fma_f32 v[28:29], v[28:29], v[14:15], 0.5 op_sel_hi:[1,0,0]
	v_pk_fma_f32 v[30:31], v[30:31], v[14:15], 0.5 op_sel_hi:[1,0,0]
	v_med3_f32 v24, v24, 1.0, v232
	v_med3_f32 v25, v25, 1.0, v232
	v_med3_f32 v26, v26, 1.0, v232
	v_med3_f32 v27, v27, 1.0, v232
	v_med3_f32 v28, v28, 1.0, v232
	v_med3_f32 v29, v29, 1.0, v232
	v_med3_f32 v30, v30, 1.0, v232
	v_med3_f32 v31, v31, 1.0, v232
	v_cvt_u32_f32_e32 v24, v24
	v_cvt_u32_f32_e32 v25, v25
	v_cvt_u32_f32_sdwa v26, v26 dst_sel:WORD_1 dst_unused:UNUSED_PAD src0_sel:DWORD
	v_cvt_u32_f32_sdwa v27, v27 dst_sel:BYTE_3 dst_unused:UNUSED_PAD src0_sel:DWORD
	v_cvt_u32_f32_e32 v28, v28
	v_cvt_u32_f32_e32 v29, v29
	v_cvt_u32_f32_sdwa v30, v30 dst_sel:WORD_1 dst_unused:UNUSED_PAD src0_sel:DWORD
	v_cvt_u32_f32_sdwa v31, v31 dst_sel:BYTE_3 dst_unused:UNUSED_PAD src0_sel:DWORD
	v_lshl_or_b32 v24, v25, 8, v24
	v_lshl_or_b32 v28, v29, 8, v28
	v_or3_b32 v24, v24, v26, v27
	v_or3_b32 v25, v28, v30, v31
	global_store_dwordx2 v[8:9], v[24:25], off offset:128
	v_or_b32_e32 v8, 16, v4
	v_mad_i64_i32 v[8:9], s[50:51], v8, s33, v[2:3]
	v_lshl_add_u64 v[8:9], v[8:9], 0, s[48:49]
	v_lshl_add_u64 v[8:9], v[8:9], 0, v[192:193]
	v_pk_mul_f32 v[16:17], v[206:207], v[144:145] op_sel_hi:[0,1]
	v_pk_mul_f32 v[18:19], v[206:207], v[146:147] op_sel_hi:[0,1]
	v_pk_mul_f32 v[20:21], v[206:207], v[140:141] op_sel_hi:[0,1]
	v_pk_mul_f32 v[22:23], v[206:207], v[142:143] op_sel_hi:[0,1]
	v_med3_f32 v16, v16, s96, v231
;     __device__ __forceinline__ void operator()(const f32x4 (&acc)[2][2][4][2], const Unit& u, int wr, int wc, int fr, int fq) const {
;     ...
;                 for (int bj = 0; bj < 2; ++bj) { const f32x4 v0 = acc[ai][bj][m][0] * sc, v1 = acc[ai][bj][m][1] * sc; unsigned q[8];
; #pragma unroll
;                     for (int j = 0; j < 4; ++j) { const float s0 = 255.0f * __builtin_amdgcn_rcpf(1.0f + __builtin_amdgcn_exp2f(-1.44269504089f * __builtin_amdgcn_fmed3f(v0[j], -30.f, 30.f))) + 0.5f,
;                                                               s1 = 255.0f * __builtin_amdgcn_rcpf(1.0f + __builtin_amdgcn_exp2f(-1.44269504089f * __builtin_amdgcn_fmed3f(v1[j], -30.f, 30.f))) + 0.5f;
;                         q[j] = (unsigned)__builtin_amdgcn_fmed3f(s0, 1.0f, 255.0f); q[4 + j] = (unsigned)__builtin_amdgcn_fmed3f(s1, 1.0f, 255.0f); }
;                     u32x2 w; w.x = q[0] | (q[1] << 8) | (q[2] << 16) | (q[3] << 24); w.y = q[4] | (q[5] << 8) | (q[6] << 16) | (q[7] << 24);
;                     *(u32x2*)(Q + row * 6144 + u.pn * BM + colt + bj * HALF) = w; } }
	v_med3_f32 v17, v17, s96, v231
	v_med3_f32 v18, v18, s96, v231
	v_med3_f32 v19, v19, s96, v231
	v_med3_f32 v20, v20, s96, v231
	v_med3_f32 v21, v21, s96, v231
	v_med3_f32 v22, v22, s96, v231
	v_med3_f32 v23, v23, s96, v231
	v_pk_mul_f32 v[16:17], v[16:17], s[98:99]
	v_pk_mul_f32 v[18:19], v[18:19], s[98:99]
	v_pk_mul_f32 v[20:21], v[20:21], s[98:99]
	v_pk_mul_f32 v[22:23], v[22:23], s[98:99]
	v_exp_f32_e32 v16, v16
	v_exp_f32_e32 v17, v17
	v_exp_f32_e32 v18, v18
	v_exp_f32_e32 v19, v19
	v_exp_f32_e32 v20, v20
	v_exp_f32_e32 v21, v21
	v_exp_f32_e32 v22, v22
	v_exp_f32_e32 v23, v23
	v_pk_add_f32 v[16:17], v[16:17], 1.0 op_sel_hi:[1,0]
	v_pk_add_f32 v[18:19], v[18:19], 1.0 op_sel_hi:[1,0]
	v_pk_add_f32 v[20:21], v[20:21], 1.0 op_sel_hi:[1,0]
	v_pk_add_f32 v[22:23], v[22:23], 1.0 op_sel_hi:[1,0]
	v_rcp_f32_e32 v16, v16
	v_rcp_f32_e32 v17, v17
	v_rcp_f32_e32 v18, v18
	v_rcp_f32_e32 v19, v19
	v_rcp_f32_e32 v20, v20
	v_rcp_f32_e32 v21, v21
	v_rcp_f32_e32 v22, v22
	v_rcp_f32_e32 v23, v23
	v_pk_fma_f32 v[16:17], v[16:17], v[14:15], 0.5 op_sel_hi:[1,0,0]
	v_pk_fma_f32 v[18:19], v[18:19], v[14:15], 0.5 op_sel_hi:[1,0,0]
	v_pk_fma_f32 v[20:21], v[20:21], v[14:15], 0.5 op_sel_hi:[1,0,0]
	v_pk_fma_f32 v[22:23], v[22:23], v[14:15], 0.5 op_sel_hi:[1,0,0]
	v_med3_f32 v16, v16, 1.0, v232
	v_med3_f32 v17, v17, 1.0, v232
	v_med3_f32 v18, v18, 1.0, v232
	v_med3_f32 v19, v19, 1.0, v232
	v_med3_f32 v20, v20, 1.0, v232
	v_med3_f32 v21, v21, 1.0, v232
	v_med3_f32 v22, v22, 1.0, v232
	v_med3_f32 v23, v23, 1.0, v232
	v_cvt_u32_f32_e32 v16, v16
	v_cvt_u32_f32_e32 v17, v17
	v_cvt_u32_f32_sdwa v18, v18 dst_sel:WORD_1 dst_unused:UNUSED_PAD src0_sel:DWORD
	v_cvt_u32_f32_sdwa v19, v19 dst_sel:BYTE_3 dst_unused:UNUSED_PAD src0_sel:DWORD
	v_cvt_u32_f32_e32 v20, v20
	v_cvt_u32_f32_e32 v21, v21
	v_cvt_u32_f32_sdwa v22, v22 dst_sel:WORD_1 dst_unused:UNUSED_PAD src0_sel:DWORD
	v_cvt_u32_f32_sdwa v23, v23 dst_sel:BYTE_3 dst_unused:UNUSED_PAD src0_sel:DWORD
	v_lshl_or_b32 v16, v17, 8, v16
	v_lshl_or_b32 v20, v21, 8, v20
	v_or3_b32 v16, v16, v18, v19
	v_or3_b32 v17, v20, v22, v23
	global_store_dwordx2 v[8:9], v[16:17], off
	v_pk_mul_f32 v[24:25], v[206:207], v[136:137] op_sel_hi:[0,1]
	v_pk_mul_f32 v[26:27], v[206:207], v[138:139] op_sel_hi:[0,1]
	v_pk_mul_f32 v[28:29], v[206:207], v[132:133] op_sel_hi:[0,1]
	v_pk_mul_f32 v[30:31], v[206:207], v[134:135] op_sel_hi:[0,1]
	v_med3_f32 v24, v24, s96, v231
	v_med3_f32 v25, v25, s96, v231
	v_med3_f32 v26, v26, s96, v231
	v_med3_f32 v27, v27, s96, v231
	v_med3_f32 v28, v28, s96, v231
	v_med3_f32 v29, v29, s96, v231
	v_med3_f32 v30, v30, s96, v231
	v_med3_f32 v31, v31, s96, v231
	v_pk_mul_f32 v[24:25], v[24:25], s[98:99]
	v_pk_mul_f32 v[26:27], v[26:27], s[98:99]
	v_pk_mul_f32 v[28:29], v[28:29], s[98:99]
	v_pk_mul_f32 v[30:31], v[30:31], s[98:99]
	v_exp_f32_e32 v24, v24
	v_exp_f32_e32 v25, v25
	v_exp_f32_e32 v26, v26
	v_exp_f32_e32 v27, v27
	v_exp_f32_e32 v28, v28
	v_exp_f32_e32 v29, v29
	v_exp_f32_e32 v30, v30
	v_exp_f32_e32 v31, v31
	v_pk_add_f32 v[24:25], v[24:25], 1.0 op_sel_hi:[1,0]
	v_pk_add_f32 v[26:27], v[26:27], 1.0 op_sel_hi:[1,0]
	v_pk_add_f32 v[28:29], v[28:29], 1.0 op_sel_hi:[1,0]
	v_pk_add_f32 v[30:31], v[30:31], 1.0 op_sel_hi:[1,0]
	v_rcp_f32_e32 v24, v24
	v_rcp_f32_e32 v25, v25
	v_rcp_f32_e32 v26, v26
	v_rcp_f32_e32 v27, v27
	v_rcp_f32_e32 v28, v28
	v_rcp_f32_e32 v29, v29
	v_rcp_f32_e32 v30, v30
	v_rcp_f32_e32 v31, v31
	v_pk_fma_f32 v[24:25], v[24:25], v[14:15], 0.5 op_sel_hi:[1,0,0]
	v_pk_fma_f32 v[26:27], v[26:27], v[14:15], 0.5 op_sel_hi:[1,0,0]
	v_pk_fma_f32 v[28:29], v[28:29], v[14:15], 0.5 op_sel_hi:[1,0,0]
	v_pk_fma_f32 v[30:31], v[30:31], v[14:15], 0.5 op_sel_hi:[1,0,0]
	v_med3_f32 v24, v24, 1.0, v232
	v_med3_f32 v25, v25, 1.0, v232
	v_med3_f32 v26, v26, 1.0, v232
	v_med3_f32 v27, v27, 1.0, v232
	v_med3_f32 v28, v28, 1.0, v232
	v_med3_f32 v29, v29, 1.0, v232
	v_med3_f32 v30, v30, 1.0, v232
	v_med3_f32 v31, v31, 1.0, v232
	v_cvt_u32_f32_e32 v24, v24
	v_cvt_u32_f32_e32 v25, v25
	v_cvt_u32_f32_sdwa v26, v26 dst_sel:WORD_1 dst_unused:UNUSED_PAD src0_sel:DWORD
	v_cvt_u32_f32_sdwa v27, v27 dst_sel:BYTE_3 dst_unused:UNUSED_PAD src0_sel:DWORD
	v_cvt_u32_f32_e32 v28, v28
	v_cvt_u32_f32_e32 v29, v29
	v_cvt_u32_f32_sdwa v30, v30 dst_sel:WORD_1 dst_unused:UNUSED_PAD src0_sel:DWORD
	v_cvt_u32_f32_sdwa v31, v31 dst_sel:BYTE_3 dst_unused:UNUSED_PAD src0_sel:DWORD
	v_lshl_or_b32 v24, v25, 8, v24
	v_lshl_or_b32 v28, v29, 8, v28
	v_or3_b32 v24, v24, v26, v27
	v_or3_b32 v25, v28, v30, v31
	global_store_dwordx2 v[8:9], v[24:25], off offset:128
	v_or_b32_e32 v8, 32, v4
	v_mad_i64_i32 v[8:9], s[50:51], v8, s33, v[2:3]
	v_lshl_add_u64 v[8:9], v[8:9], 0, s[48:49]
	v_lshl_add_u64 v[8:9], v[8:9], 0, v[192:193]
	v_pk_mul_f32 v[16:17], v[206:207], v[128:129] op_sel_hi:[0,1]
	v_pk_mul_f32 v[18:19], v[206:207], v[130:131] op_sel_hi:[0,1]
	v_pk_mul_f32 v[20:21], v[206:207], v[124:125] op_sel_hi:[0,1]
	v_pk_mul_f32 v[22:23], v[206:207], v[126:127] op_sel_hi:[0,1]
	v_med3_f32 v16, v16, s96, v231
	v_med3_f32 v17, v17, s96, v231
	v_med3_f32 v18, v18, s96, v231
	v_med3_f32 v19, v19, s96, v231
	v_med3_f32 v20, v20, s96, v231
	v_med3_f32 v21, v21, s96, v231
	v_med3_f32 v22, v22, s96, v231
	v_med3_f32 v23, v23, s96, v231
	v_pk_mul_f32 v[16:17], v[16:17], s[98:99]
	v_pk_mul_f32 v[18:19], v[18:19], s[98:99]
	v_pk_mul_f32 v[20:21], v[20:21], s[98:99]
	v_pk_mul_f32 v[22:23], v[22:23], s[98:99]
	v_exp_f32_e32 v16, v16
	v_exp_f32_e32 v17, v17
	v_exp_f32_e32 v18, v18
	v_exp_f32_e32 v19, v19
	v_exp_f32_e32 v20, v20
	v_exp_f32_e32 v21, v21
	v_exp_f32_e32 v22, v22
	v_exp_f32_e32 v23, v23
	v_pk_add_f32 v[16:17], v[16:17], 1.0 op_sel_hi:[1,0]
;     __device__ __forceinline__ void operator()(const f32x4 (&acc)[2][2][4][2], const Unit& u, int wr, int wc, int fr, int fq) const {
;     ...
;                 for (int bj = 0; bj < 2; ++bj) { const f32x4 v0 = acc[ai][bj][m][0] * sc, v1 = acc[ai][bj][m][1] * sc; unsigned q[8];
; #pragma unroll
;                     for (int j = 0; j < 4; ++j) { const float s0 = 255.0f * __builtin_amdgcn_rcpf(1.0f + __builtin_amdgcn_exp2f(-1.44269504089f * __builtin_amdgcn_fmed3f(v0[j], -30.f, 30.f))) + 0.5f,
;                                                               s1 = 255.0f * __builtin_amdgcn_rcpf(1.0f + __builtin_amdgcn_exp2f(-1.44269504089f * __builtin_amdgcn_fmed3f(v1[j], -30.f, 30.f))) + 0.5f;
;                         q[j] = (unsigned)__builtin_amdgcn_fmed3f(s0, 1.0f, 255.0f); q[4 + j] = (unsigned)__builtin_amdgcn_fmed3f(s1, 1.0f, 255.0f); }
;                     u32x2 w; w.x = q[0] | (q[1] << 8) | (q[2] << 16) | (q[3] << 24); w.y = q[4] | (q[5] << 8) | (q[6] << 16) | (q[7] << 24);
;                     *(u32x2*)(Q + row * 6144 + u.pn * BM + colt + bj * HALF) = w; } }
	v_pk_add_f32 v[18:19], v[18:19], 1.0 op_sel_hi:[1,0]
	v_pk_add_f32 v[20:21], v[20:21], 1.0 op_sel_hi:[1,0]
	v_pk_add_f32 v[22:23], v[22:23], 1.0 op_sel_hi:[1,0]
	v_rcp_f32_e32 v16, v16
	v_rcp_f32_e32 v17, v17
	v_rcp_f32_e32 v18, v18
	v_rcp_f32_e32 v19, v19
	v_rcp_f32_e32 v20, v20
	v_rcp_f32_e32 v21, v21
	v_rcp_f32_e32 v22, v22
	v_rcp_f32_e32 v23, v23
	v_pk_fma_f32 v[16:17], v[16:17], v[14:15], 0.5 op_sel_hi:[1,0,0]
	v_pk_fma_f32 v[18:19], v[18:19], v[14:15], 0.5 op_sel_hi:[1,0,0]
	v_pk_fma_f32 v[20:21], v[20:21], v[14:15], 0.5 op_sel_hi:[1,0,0]
	v_pk_fma_f32 v[22:23], v[22:23], v[14:15], 0.5 op_sel_hi:[1,0,0]
	v_med3_f32 v16, v16, 1.0, v232
	v_med3_f32 v17, v17, 1.0, v232
	v_med3_f32 v18, v18, 1.0, v232
	v_med3_f32 v19, v19, 1.0, v232
	v_med3_f32 v20, v20, 1.0, v232
	v_med3_f32 v21, v21, 1.0, v232
	v_med3_f32 v22, v22, 1.0, v232
	v_med3_f32 v23, v23, 1.0, v232
	v_cvt_u32_f32_e32 v16, v16
	v_cvt_u32_f32_e32 v17, v17
	v_cvt_u32_f32_sdwa v18, v18 dst_sel:WORD_1 dst_unused:UNUSED_PAD src0_sel:DWORD
	v_cvt_u32_f32_sdwa v19, v19 dst_sel:BYTE_3 dst_unused:UNUSED_PAD src0_sel:DWORD
	v_cvt_u32_f32_e32 v20, v20
	v_cvt_u32_f32_e32 v21, v21
	v_cvt_u32_f32_sdwa v22, v22 dst_sel:WORD_1 dst_unused:UNUSED_PAD src0_sel:DWORD
	v_cvt_u32_f32_sdwa v23, v23 dst_sel:BYTE_3 dst_unused:UNUSED_PAD src0_sel:DWORD
	v_lshl_or_b32 v16, v17, 8, v16
	v_lshl_or_b32 v20, v21, 8, v20
	v_or3_b32 v16, v16, v18, v19
	v_or3_b32 v17, v20, v22, v23
	global_store_dwordx2 v[8:9], v[16:17], off
	v_pk_mul_f32 v[24:25], v[206:207], v[120:121] op_sel_hi:[0,1]
	v_pk_mul_f32 v[26:27], v[206:207], v[122:123] op_sel_hi:[0,1]
	v_pk_mul_f32 v[28:29], v[206:207], v[116:117] op_sel_hi:[0,1]
	v_pk_mul_f32 v[30:31], v[206:207], v[118:119] op_sel_hi:[0,1]
	v_med3_f32 v24, v24, s96, v231
	v_med3_f32 v25, v25, s96, v231
	v_med3_f32 v26, v26, s96, v231
	v_med3_f32 v27, v27, s96, v231
	v_med3_f32 v28, v28, s96, v231
	v_med3_f32 v29, v29, s96, v231
	v_med3_f32 v30, v30, s96, v231
	v_med3_f32 v31, v31, s96, v231
	v_pk_mul_f32 v[24:25], v[24:25], s[98:99]
	v_pk_mul_f32 v[26:27], v[26:27], s[98:99]
	v_pk_mul_f32 v[28:29], v[28:29], s[98:99]
	v_pk_mul_f32 v[30:31], v[30:31], s[98:99]
	v_exp_f32_e32 v24, v24
	v_exp_f32_e32 v25, v25
	v_exp_f32_e32 v26, v26
	v_exp_f32_e32 v27, v27
	v_exp_f32_e32 v28, v28
	v_exp_f32_e32 v29, v29
	v_exp_f32_e32 v30, v30
	v_exp_f32_e32 v31, v31
	v_pk_add_f32 v[24:25], v[24:25], 1.0 op_sel_hi:[1,0]
	v_pk_add_f32 v[26:27], v[26:27], 1.0 op_sel_hi:[1,0]
	v_pk_add_f32 v[28:29], v[28:29], 1.0 op_sel_hi:[1,0]
	v_pk_add_f32 v[30:31], v[30:31], 1.0 op_sel_hi:[1,0]
	v_rcp_f32_e32 v24, v24
	v_rcp_f32_e32 v25, v25
	v_rcp_f32_e32 v26, v26
	v_rcp_f32_e32 v27, v27
	v_rcp_f32_e32 v28, v28
	v_rcp_f32_e32 v29, v29
	v_rcp_f32_e32 v30, v30
	v_rcp_f32_e32 v31, v31
	v_pk_fma_f32 v[24:25], v[24:25], v[14:15], 0.5 op_sel_hi:[1,0,0]
	v_pk_fma_f32 v[26:27], v[26:27], v[14:15], 0.5 op_sel_hi:[1,0,0]
	v_pk_fma_f32 v[28:29], v[28:29], v[14:15], 0.5 op_sel_hi:[1,0,0]
	v_pk_fma_f32 v[30:31], v[30:31], v[14:15], 0.5 op_sel_hi:[1,0,0]
	v_med3_f32 v24, v24, 1.0, v232
	v_med3_f32 v25, v25, 1.0, v232
	v_med3_f32 v26, v26, 1.0, v232
	v_med3_f32 v27, v27, 1.0, v232
	v_med3_f32 v28, v28, 1.0, v232
	v_med3_f32 v29, v29, 1.0, v232
	v_med3_f32 v30, v30, 1.0, v232
	v_med3_f32 v31, v31, 1.0, v232
	v_cvt_u32_f32_e32 v24, v24
	v_cvt_u32_f32_e32 v25, v25
	v_cvt_u32_f32_sdwa v26, v26 dst_sel:WORD_1 dst_unused:UNUSED_PAD src0_sel:DWORD
	v_cvt_u32_f32_sdwa v27, v27 dst_sel:BYTE_3 dst_unused:UNUSED_PAD src0_sel:DWORD
	v_cvt_u32_f32_e32 v28, v28
	v_cvt_u32_f32_e32 v29, v29
	v_cvt_u32_f32_sdwa v30, v30 dst_sel:WORD_1 dst_unused:UNUSED_PAD src0_sel:DWORD
	v_cvt_u32_f32_sdwa v31, v31 dst_sel:BYTE_3 dst_unused:UNUSED_PAD src0_sel:DWORD
	v_lshl_or_b32 v24, v25, 8, v24
	v_lshl_or_b32 v28, v29, 8, v28
	v_or3_b32 v24, v24, v26, v27
	v_or3_b32 v25, v28, v30, v31
	global_store_dwordx2 v[8:9], v[24:25], off offset:128
	v_or_b32_e32 v8, 48, v4
	v_mad_i64_i32 v[8:9], s[50:51], v8, s33, v[2:3]
	v_lshl_add_u64 v[8:9], v[8:9], 0, s[48:49]
	v_lshl_add_u64 v[8:9], v[8:9], 0, v[192:193]
	v_pk_mul_f32 v[16:17], v[206:207], v[112:113] op_sel_hi:[0,1]
	v_pk_mul_f32 v[18:19], v[206:207], v[114:115] op_sel_hi:[0,1]
	v_pk_mul_f32 v[20:21], v[206:207], v[108:109] op_sel_hi:[0,1]
	v_pk_mul_f32 v[22:23], v[206:207], v[110:111] op_sel_hi:[0,1]
	v_med3_f32 v16, v16, s96, v231
	v_med3_f32 v17, v17, s96, v231
	v_med3_f32 v18, v18, s96, v231
	v_med3_f32 v19, v19, s96, v231
	v_med3_f32 v20, v20, s96, v231
	v_med3_f32 v21, v21, s96, v231
	v_med3_f32 v22, v22, s96, v231
	v_med3_f32 v23, v23, s96, v231
	v_pk_mul_f32 v[16:17], v[16:17], s[98:99]
	v_pk_mul_f32 v[18:19], v[18:19], s[98:99]
	v_pk_mul_f32 v[20:21], v[20:21], s[98:99]
	v_pk_mul_f32 v[22:23], v[22:23], s[98:99]
	v_exp_f32_e32 v16, v16
	v_exp_f32_e32 v17, v17
	v_exp_f32_e32 v18, v18
	v_exp_f32_e32 v19, v19
	v_exp_f32_e32 v20, v20
	v_exp_f32_e32 v21, v21
	v_exp_f32_e32 v22, v22
	v_exp_f32_e32 v23, v23
	v_pk_add_f32 v[16:17], v[16:17], 1.0 op_sel_hi:[1,0]
	v_pk_add_f32 v[18:19], v[18:19], 1.0 op_sel_hi:[1,0]
	v_pk_add_f32 v[20:21], v[20:21], 1.0 op_sel_hi:[1,0]
	v_pk_add_f32 v[22:23], v[22:23], 1.0 op_sel_hi:[1,0]
	v_rcp_f32_e32 v16, v16
	v_rcp_f32_e32 v17, v17
	v_rcp_f32_e32 v18, v18
	v_rcp_f32_e32 v19, v19
	v_rcp_f32_e32 v20, v20
	v_rcp_f32_e32 v21, v21
	v_rcp_f32_e32 v22, v22
	v_rcp_f32_e32 v23, v23
	v_pk_fma_f32 v[16:17], v[16:17], v[14:15], 0.5 op_sel_hi:[1,0,0]
	v_pk_fma_f32 v[18:19], v[18:19], v[14:15], 0.5 op_sel_hi:[1,0,0]
	v_pk_fma_f32 v[20:21], v[20:21], v[14:15], 0.5 op_sel_hi:[1,0,0]
	v_pk_fma_f32 v[22:23], v[22:23], v[14:15], 0.5 op_sel_hi:[1,0,0]
	v_med3_f32 v16, v16, 1.0, v232
;     __device__ __forceinline__ void operator()(const f32x4 (&acc)[2][2][4][2], const Unit& u, int wr, int wc, int fr, int fq) const {
;     ...
;                 for (int bj = 0; bj < 2; ++bj) { const f32x4 v0 = acc[ai][bj][m][0] * sc, v1 = acc[ai][bj][m][1] * sc; unsigned q[8];
; #pragma unroll
;                     for (int j = 0; j < 4; ++j) { const float s0 = 255.0f * __builtin_amdgcn_rcpf(1.0f + __builtin_amdgcn_exp2f(-1.44269504089f * __builtin_amdgcn_fmed3f(v0[j], -30.f, 30.f))) + 0.5f,
;                                                               s1 = 255.0f * __builtin_amdgcn_rcpf(1.0f + __builtin_amdgcn_exp2f(-1.44269504089f * __builtin_amdgcn_fmed3f(v1[j], -30.f, 30.f))) + 0.5f;
;                         q[j] = (unsigned)__builtin_amdgcn_fmed3f(s0, 1.0f, 255.0f); q[4 + j] = (unsigned)__builtin_amdgcn_fmed3f(s1, 1.0f, 255.0f); }
;                     u32x2 w; w.x = q[0] | (q[1] << 8) | (q[2] << 16) | (q[3] << 24); w.y = q[4] | (q[5] << 8) | (q[6] << 16) | (q[7] << 24);
;                     *(u32x2*)(Q + row * 6144 + u.pn * BM + colt + bj * HALF) = w; } }
	v_med3_f32 v17, v17, 1.0, v232
	v_med3_f32 v18, v18, 1.0, v232
	v_med3_f32 v19, v19, 1.0, v232
	v_med3_f32 v20, v20, 1.0, v232
	v_med3_f32 v21, v21, 1.0, v232
	v_med3_f32 v22, v22, 1.0, v232
	v_med3_f32 v23, v23, 1.0, v232
	v_cvt_u32_f32_e32 v16, v16
	v_cvt_u32_f32_e32 v17, v17
	v_cvt_u32_f32_sdwa v18, v18 dst_sel:WORD_1 dst_unused:UNUSED_PAD src0_sel:DWORD
	v_cvt_u32_f32_sdwa v19, v19 dst_sel:BYTE_3 dst_unused:UNUSED_PAD src0_sel:DWORD
	v_cvt_u32_f32_e32 v20, v20
	v_cvt_u32_f32_e32 v21, v21
	v_cvt_u32_f32_sdwa v22, v22 dst_sel:WORD_1 dst_unused:UNUSED_PAD src0_sel:DWORD
	v_cvt_u32_f32_sdwa v23, v23 dst_sel:BYTE_3 dst_unused:UNUSED_PAD src0_sel:DWORD
	v_lshl_or_b32 v16, v17, 8, v16
	v_lshl_or_b32 v20, v21, 8, v20
	v_or3_b32 v16, v16, v18, v19
	v_or3_b32 v17, v20, v22, v23
	global_store_dwordx2 v[8:9], v[16:17], off
	v_pk_mul_f32 v[24:25], v[206:207], v[104:105] op_sel_hi:[0,1]
	v_pk_mul_f32 v[26:27], v[206:207], v[106:107] op_sel_hi:[0,1]
	v_pk_mul_f32 v[28:29], v[206:207], v[100:101] op_sel_hi:[0,1]
	v_pk_mul_f32 v[30:31], v[206:207], v[102:103] op_sel_hi:[0,1]
	v_med3_f32 v24, v24, s96, v231
	v_med3_f32 v25, v25, s96, v231
	v_med3_f32 v26, v26, s96, v231
	v_med3_f32 v27, v27, s96, v231
	v_med3_f32 v28, v28, s96, v231
	v_med3_f32 v29, v29, s96, v231
	v_med3_f32 v30, v30, s96, v231
	v_med3_f32 v31, v31, s96, v231
	v_pk_mul_f32 v[24:25], v[24:25], s[98:99]
	v_pk_mul_f32 v[26:27], v[26:27], s[98:99]
	v_pk_mul_f32 v[28:29], v[28:29], s[98:99]
	v_pk_mul_f32 v[30:31], v[30:31], s[98:99]
	v_exp_f32_e32 v24, v24
	v_exp_f32_e32 v25, v25
	v_exp_f32_e32 v26, v26
	v_exp_f32_e32 v27, v27
	v_exp_f32_e32 v28, v28
	v_exp_f32_e32 v29, v29
	v_exp_f32_e32 v30, v30
	v_exp_f32_e32 v31, v31
	v_pk_add_f32 v[24:25], v[24:25], 1.0 op_sel_hi:[1,0]
	v_pk_add_f32 v[26:27], v[26:27], 1.0 op_sel_hi:[1,0]
	v_pk_add_f32 v[28:29], v[28:29], 1.0 op_sel_hi:[1,0]
	v_pk_add_f32 v[30:31], v[30:31], 1.0 op_sel_hi:[1,0]
	v_rcp_f32_e32 v24, v24
	v_rcp_f32_e32 v25, v25
	v_rcp_f32_e32 v26, v26
	v_rcp_f32_e32 v27, v27
	v_rcp_f32_e32 v28, v28
	v_rcp_f32_e32 v29, v29
	v_rcp_f32_e32 v30, v30
	v_rcp_f32_e32 v31, v31
	v_pk_fma_f32 v[24:25], v[24:25], v[14:15], 0.5 op_sel_hi:[1,0,0]
	v_pk_fma_f32 v[26:27], v[26:27], v[14:15], 0.5 op_sel_hi:[1,0,0]
	v_pk_fma_f32 v[28:29], v[28:29], v[14:15], 0.5 op_sel_hi:[1,0,0]
	v_pk_fma_f32 v[30:31], v[30:31], v[14:15], 0.5 op_sel_hi:[1,0,0]
	v_med3_f32 v24, v24, 1.0, v232
	v_med3_f32 v25, v25, 1.0, v232
	v_med3_f32 v26, v26, 1.0, v232
	v_med3_f32 v27, v27, 1.0, v232
	v_med3_f32 v28, v28, 1.0, v232
	v_med3_f32 v29, v29, 1.0, v232
	v_med3_f32 v30, v30, 1.0, v232
	v_med3_f32 v31, v31, 1.0, v232
	v_cvt_u32_f32_e32 v24, v24
	v_cvt_u32_f32_e32 v25, v25
	v_cvt_u32_f32_sdwa v26, v26 dst_sel:WORD_1 dst_unused:UNUSED_PAD src0_sel:DWORD
	v_cvt_u32_f32_sdwa v27, v27 dst_sel:BYTE_3 dst_unused:UNUSED_PAD src0_sel:DWORD
	v_cvt_u32_f32_e32 v28, v28
	v_cvt_u32_f32_e32 v29, v29
	v_cvt_u32_f32_sdwa v30, v30 dst_sel:WORD_1 dst_unused:UNUSED_PAD src0_sel:DWORD
	v_cvt_u32_f32_sdwa v31, v31 dst_sel:BYTE_3 dst_unused:UNUSED_PAD src0_sel:DWORD
	v_lshl_or_b32 v24, v25, 8, v24
	v_lshl_or_b32 v28, v29, 8, v28
	v_or3_b32 v24, v24, v26, v27
	v_or3_b32 v25, v28, v30, v31
	global_store_dwordx2 v[8:9], v[24:25], off offset:128
	v_add_u32_e32 v8, 0x80, v4
	v_mad_i64_i32 v[8:9], s[50:51], v8, s33, v[2:3]
	v_lshl_add_u64 v[8:9], v[8:9], 0, s[48:49]
	v_lshl_add_u64 v[8:9], v[8:9], 0, v[192:193]
	v_pk_mul_f32 v[16:17], v[206:207], v[96:97] op_sel_hi:[0,1]
	v_pk_mul_f32 v[18:19], v[206:207], v[98:99] op_sel_hi:[0,1]
	v_pk_mul_f32 v[20:21], v[206:207], v[92:93] op_sel_hi:[0,1]
	v_pk_mul_f32 v[22:23], v[206:207], v[94:95] op_sel_hi:[0,1]
	v_med3_f32 v16, v16, s96, v231
	v_med3_f32 v17, v17, s96, v231
	v_med3_f32 v18, v18, s96, v231
	v_med3_f32 v19, v19, s96, v231
	v_med3_f32 v20, v20, s96, v231
	v_med3_f32 v21, v21, s96, v231
	v_med3_f32 v22, v22, s96, v231
	v_med3_f32 v23, v23, s96, v231
	v_pk_mul_f32 v[16:17], v[16:17], s[98:99]
	v_pk_mul_f32 v[18:19], v[18:19], s[98:99]
	v_pk_mul_f32 v[20:21], v[20:21], s[98:99]
	v_pk_mul_f32 v[22:23], v[22:23], s[98:99]
	v_exp_f32_e32 v16, v16
	v_exp_f32_e32 v17, v17
	v_exp_f32_e32 v18, v18
	v_exp_f32_e32 v19, v19
	v_exp_f32_e32 v20, v20
	v_exp_f32_e32 v21, v21
	v_exp_f32_e32 v22, v22
	v_exp_f32_e32 v23, v23
	v_pk_add_f32 v[16:17], v[16:17], 1.0 op_sel_hi:[1,0]
	v_pk_add_f32 v[18:19], v[18:19], 1.0 op_sel_hi:[1,0]
	v_pk_add_f32 v[20:21], v[20:21], 1.0 op_sel_hi:[1,0]
	v_pk_add_f32 v[22:23], v[22:23], 1.0 op_sel_hi:[1,0]
	v_rcp_f32_e32 v16, v16
	v_rcp_f32_e32 v17, v17
	v_rcp_f32_e32 v18, v18
	v_rcp_f32_e32 v19, v19
	v_rcp_f32_e32 v20, v20
	v_rcp_f32_e32 v21, v21
	v_rcp_f32_e32 v22, v22
	v_rcp_f32_e32 v23, v23
	v_pk_fma_f32 v[16:17], v[16:17], v[14:15], 0.5 op_sel_hi:[1,0,0]
	v_pk_fma_f32 v[18:19], v[18:19], v[14:15], 0.5 op_sel_hi:[1,0,0]
	v_pk_fma_f32 v[20:21], v[20:21], v[14:15], 0.5 op_sel_hi:[1,0,0]
	v_pk_fma_f32 v[22:23], v[22:23], v[14:15], 0.5 op_sel_hi:[1,0,0]
	v_med3_f32 v16, v16, 1.0, v232
	v_med3_f32 v17, v17, 1.0, v232
	v_med3_f32 v18, v18, 1.0, v232
	v_med3_f32 v19, v19, 1.0, v232
	v_med3_f32 v20, v20, 1.0, v232
	v_med3_f32 v21, v21, 1.0, v232
	v_med3_f32 v22, v22, 1.0, v232
	v_med3_f32 v23, v23, 1.0, v232
	v_cvt_u32_f32_e32 v16, v16
	v_cvt_u32_f32_e32 v17, v17
	v_cvt_u32_f32_sdwa v18, v18 dst_sel:WORD_1 dst_unused:UNUSED_PAD src0_sel:DWORD
	v_cvt_u32_f32_sdwa v19, v19 dst_sel:BYTE_3 dst_unused:UNUSED_PAD src0_sel:DWORD
	v_cvt_u32_f32_e32 v20, v20
	v_cvt_u32_f32_e32 v21, v21
	v_cvt_u32_f32_sdwa v22, v22 dst_sel:WORD_1 dst_unused:UNUSED_PAD src0_sel:DWORD
	v_cvt_u32_f32_sdwa v23, v23 dst_sel:BYTE_3 dst_unused:UNUSED_PAD src0_sel:DWORD
;     __device__ __forceinline__ void operator()(const f32x4 (&acc)[2][2][4][2], const Unit& u, int wr, int wc, int fr, int fq) const {
;     ...
;                 for (int bj = 0; bj < 2; ++bj) { const f32x4 v0 = acc[ai][bj][m][0] * sc, v1 = acc[ai][bj][m][1] * sc; unsigned q[8];
; #pragma unroll
;                     for (int j = 0; j < 4; ++j) { const float s0 = 255.0f * __builtin_amdgcn_rcpf(1.0f + __builtin_amdgcn_exp2f(-1.44269504089f * __builtin_amdgcn_fmed3f(v0[j], -30.f, 30.f))) + 0.5f,
;                                                               s1 = 255.0f * __builtin_amdgcn_rcpf(1.0f + __builtin_amdgcn_exp2f(-1.44269504089f * __builtin_amdgcn_fmed3f(v1[j], -30.f, 30.f))) + 0.5f;
;                         q[j] = (unsigned)__builtin_amdgcn_fmed3f(s0, 1.0f, 255.0f); q[4 + j] = (unsigned)__builtin_amdgcn_fmed3f(s1, 1.0f, 255.0f); }
;                     u32x2 w; w.x = q[0] | (q[1] << 8) | (q[2] << 16) | (q[3] << 24); w.y = q[4] | (q[5] << 8) | (q[6] << 16) | (q[7] << 24);
;                     *(u32x2*)(Q + row * 6144 + u.pn * BM + colt + bj * HALF) = w; } }
	v_lshl_or_b32 v16, v17, 8, v16
	v_lshl_or_b32 v20, v21, 8, v20
	v_or3_b32 v16, v16, v18, v19
	v_or3_b32 v17, v20, v22, v23
	global_store_dwordx2 v[8:9], v[16:17], off
	v_pk_mul_f32 v[24:25], v[206:207], v[88:89] op_sel_hi:[0,1]
	v_pk_mul_f32 v[26:27], v[206:207], v[90:91] op_sel_hi:[0,1]
	v_pk_mul_f32 v[28:29], v[206:207], v[84:85] op_sel_hi:[0,1]
	v_pk_mul_f32 v[30:31], v[206:207], v[86:87] op_sel_hi:[0,1]
	v_med3_f32 v24, v24, s96, v231
	v_med3_f32 v25, v25, s96, v231
	v_med3_f32 v26, v26, s96, v231
	v_med3_f32 v27, v27, s96, v231
	v_med3_f32 v28, v28, s96, v231
	v_med3_f32 v29, v29, s96, v231
	v_med3_f32 v30, v30, s96, v231
	v_med3_f32 v31, v31, s96, v231
	v_pk_mul_f32 v[24:25], v[24:25], s[98:99]
	v_pk_mul_f32 v[26:27], v[26:27], s[98:99]
	v_pk_mul_f32 v[28:29], v[28:29], s[98:99]
	v_pk_mul_f32 v[30:31], v[30:31], s[98:99]
	v_exp_f32_e32 v24, v24
	v_exp_f32_e32 v25, v25
	v_exp_f32_e32 v26, v26
	v_exp_f32_e32 v27, v27
	v_exp_f32_e32 v28, v28
	v_exp_f32_e32 v29, v29
	v_exp_f32_e32 v30, v30
	v_exp_f32_e32 v31, v31
	v_pk_add_f32 v[24:25], v[24:25], 1.0 op_sel_hi:[1,0]
	v_pk_add_f32 v[26:27], v[26:27], 1.0 op_sel_hi:[1,0]
	v_pk_add_f32 v[28:29], v[28:29], 1.0 op_sel_hi:[1,0]
	v_pk_add_f32 v[30:31], v[30:31], 1.0 op_sel_hi:[1,0]
	v_rcp_f32_e32 v24, v24
	v_rcp_f32_e32 v25, v25
	v_rcp_f32_e32 v26, v26
	v_rcp_f32_e32 v27, v27
	v_rcp_f32_e32 v28, v28
	v_rcp_f32_e32 v29, v29
	v_rcp_f32_e32 v30, v30
	v_rcp_f32_e32 v31, v31
	v_pk_fma_f32 v[24:25], v[24:25], v[14:15], 0.5 op_sel_hi:[1,0,0]
	v_pk_fma_f32 v[26:27], v[26:27], v[14:15], 0.5 op_sel_hi:[1,0,0]
	v_pk_fma_f32 v[28:29], v[28:29], v[14:15], 0.5 op_sel_hi:[1,0,0]
	v_pk_fma_f32 v[30:31], v[30:31], v[14:15], 0.5 op_sel_hi:[1,0,0]
	v_med3_f32 v24, v24, 1.0, v232
	v_med3_f32 v25, v25, 1.0, v232
	v_med3_f32 v26, v26, 1.0, v232
	v_med3_f32 v27, v27, 1.0, v232
	v_med3_f32 v28, v28, 1.0, v232
	v_med3_f32 v29, v29, 1.0, v232
	v_med3_f32 v30, v30, 1.0, v232
	v_med3_f32 v31, v31, 1.0, v232
	v_cvt_u32_f32_e32 v24, v24
	v_cvt_u32_f32_e32 v25, v25
	v_cvt_u32_f32_sdwa v26, v26 dst_sel:WORD_1 dst_unused:UNUSED_PAD src0_sel:DWORD
	v_cvt_u32_f32_sdwa v27, v27 dst_sel:BYTE_3 dst_unused:UNUSED_PAD src0_sel:DWORD
	v_cvt_u32_f32_e32 v28, v28
	v_cvt_u32_f32_e32 v29, v29
	v_cvt_u32_f32_sdwa v30, v30 dst_sel:WORD_1 dst_unused:UNUSED_PAD src0_sel:DWORD
	v_cvt_u32_f32_sdwa v31, v31 dst_sel:BYTE_3 dst_unused:UNUSED_PAD src0_sel:DWORD
	v_lshl_or_b32 v24, v25, 8, v24
	v_lshl_or_b32 v28, v29, 8, v28
	v_or3_b32 v24, v24, v26, v27
	v_or3_b32 v25, v28, v30, v31
	global_store_dwordx2 v[8:9], v[24:25], off offset:128
	v_add_u32_e32 v8, 0x90, v4
	v_mad_i64_i32 v[8:9], s[50:51], v8, s33, v[2:3]
	v_lshl_add_u64 v[8:9], v[8:9], 0, s[48:49]
	v_lshl_add_u64 v[8:9], v[8:9], 0, v[192:193]
	v_pk_mul_f32 v[16:17], v[206:207], v[80:81] op_sel_hi:[0,1]
	v_pk_mul_f32 v[18:19], v[206:207], v[82:83] op_sel_hi:[0,1]
	v_pk_mul_f32 v[20:21], v[206:207], v[76:77] op_sel_hi:[0,1]
	v_pk_mul_f32 v[22:23], v[206:207], v[78:79] op_sel_hi:[0,1]
	v_med3_f32 v16, v16, s96, v231
	v_med3_f32 v17, v17, s96, v231
	v_med3_f32 v18, v18, s96, v231
	v_med3_f32 v19, v19, s96, v231
	v_med3_f32 v20, v20, s96, v231
	v_med3_f32 v21, v21, s96, v231
	v_med3_f32 v22, v22, s96, v231
	v_med3_f32 v23, v23, s96, v231
	v_pk_mul_f32 v[16:17], v[16:17], s[98:99]
	v_pk_mul_f32 v[18:19], v[18:19], s[98:99]
	v_pk_mul_f32 v[20:21], v[20:21], s[98:99]
	v_pk_mul_f32 v[22:23], v[22:23], s[98:99]
	v_exp_f32_e32 v16, v16
	v_exp_f32_e32 v17, v17
	v_exp_f32_e32 v18, v18
	v_exp_f32_e32 v19, v19
	v_exp_f32_e32 v20, v20
	v_exp_f32_e32 v21, v21
	v_exp_f32_e32 v22, v22
	v_exp_f32_e32 v23, v23
	v_pk_add_f32 v[16:17], v[16:17], 1.0 op_sel_hi:[1,0]
	v_pk_add_f32 v[18:19], v[18:19], 1.0 op_sel_hi:[1,0]
	v_pk_add_f32 v[20:21], v[20:21], 1.0 op_sel_hi:[1,0]
	v_pk_add_f32 v[22:23], v[22:23], 1.0 op_sel_hi:[1,0]
	v_rcp_f32_e32 v16, v16
	v_rcp_f32_e32 v17, v17
	v_rcp_f32_e32 v18, v18
	v_rcp_f32_e32 v19, v19
	v_rcp_f32_e32 v20, v20
	v_rcp_f32_e32 v21, v21
	v_rcp_f32_e32 v22, v22
	v_rcp_f32_e32 v23, v23
	v_pk_fma_f32 v[16:17], v[16:17], v[14:15], 0.5 op_sel_hi:[1,0,0]
	v_pk_fma_f32 v[18:19], v[18:19], v[14:15], 0.5 op_sel_hi:[1,0,0]
	v_pk_fma_f32 v[20:21], v[20:21], v[14:15], 0.5 op_sel_hi:[1,0,0]
	v_pk_fma_f32 v[22:23], v[22:23], v[14:15], 0.5 op_sel_hi:[1,0,0]
	v_med3_f32 v16, v16, 1.0, v232
	v_med3_f32 v17, v17, 1.0, v232
	v_med3_f32 v18, v18, 1.0, v232
	v_med3_f32 v19, v19, 1.0, v232
	v_med3_f32 v20, v20, 1.0, v232
	v_med3_f32 v21, v21, 1.0, v232
	v_med3_f32 v22, v22, 1.0, v232
	v_med3_f32 v23, v23, 1.0, v232
	v_cvt_u32_f32_e32 v16, v16
	v_cvt_u32_f32_e32 v17, v17
	v_cvt_u32_f32_sdwa v18, v18 dst_sel:WORD_1 dst_unused:UNUSED_PAD src0_sel:DWORD
	v_cvt_u32_f32_sdwa v19, v19 dst_sel:BYTE_3 dst_unused:UNUSED_PAD src0_sel:DWORD
	v_cvt_u32_f32_e32 v20, v20
	v_cvt_u32_f32_e32 v21, v21
	v_cvt_u32_f32_sdwa v22, v22 dst_sel:WORD_1 dst_unused:UNUSED_PAD src0_sel:DWORD
	v_cvt_u32_f32_sdwa v23, v23 dst_sel:BYTE_3 dst_unused:UNUSED_PAD src0_sel:DWORD
	v_lshl_or_b32 v16, v17, 8, v16
	v_lshl_or_b32 v20, v21, 8, v20
	v_or3_b32 v16, v16, v18, v19
	v_or3_b32 v17, v20, v22, v23
	global_store_dwordx2 v[8:9], v[16:17], off
	v_pk_mul_f32 v[24:25], v[206:207], v[72:73] op_sel_hi:[0,1]
	v_pk_mul_f32 v[26:27], v[206:207], v[74:75] op_sel_hi:[0,1]
	v_pk_mul_f32 v[28:29], v[206:207], v[68:69] op_sel_hi:[0,1]
	v_pk_mul_f32 v[30:31], v[206:207], v[70:71] op_sel_hi:[0,1]
	v_med3_f32 v24, v24, s96, v231
	v_med3_f32 v25, v25, s96, v231
	v_med3_f32 v26, v26, s96, v231
	v_med3_f32 v27, v27, s96, v231
	v_med3_f32 v28, v28, s96, v231
	v_med3_f32 v29, v29, s96, v231
	v_med3_f32 v30, v30, s96, v231
	v_med3_f32 v31, v31, s96, v231
;     __device__ __forceinline__ void operator()(const f32x4 (&acc)[2][2][4][2], const Unit& u, int wr, int wc, int fr, int fq) const {
;     ...
;                 for (int bj = 0; bj < 2; ++bj) { const f32x4 v0 = acc[ai][bj][m][0] * sc, v1 = acc[ai][bj][m][1] * sc; unsigned q[8];
; #pragma unroll
;                     for (int j = 0; j < 4; ++j) { const float s0 = 255.0f * __builtin_amdgcn_rcpf(1.0f + __builtin_amdgcn_exp2f(-1.44269504089f * __builtin_amdgcn_fmed3f(v0[j], -30.f, 30.f))) + 0.5f,
;                                                               s1 = 255.0f * __builtin_amdgcn_rcpf(1.0f + __builtin_amdgcn_exp2f(-1.44269504089f * __builtin_amdgcn_fmed3f(v1[j], -30.f, 30.f))) + 0.5f;
;                         q[j] = (unsigned)__builtin_amdgcn_fmed3f(s0, 1.0f, 255.0f); q[4 + j] = (unsigned)__builtin_amdgcn_fmed3f(s1, 1.0f, 255.0f); }
;                     u32x2 w; w.x = q[0] | (q[1] << 8) | (q[2] << 16) | (q[3] << 24); w.y = q[4] | (q[5] << 8) | (q[6] << 16) | (q[7] << 24);
;                     *(u32x2*)(Q + row * 6144 + u.pn * BM + colt + bj * HALF) = w; } }
	v_pk_mul_f32 v[24:25], v[24:25], s[98:99]
	v_pk_mul_f32 v[26:27], v[26:27], s[98:99]
	v_pk_mul_f32 v[28:29], v[28:29], s[98:99]
	v_pk_mul_f32 v[30:31], v[30:31], s[98:99]
	v_exp_f32_e32 v24, v24
	v_exp_f32_e32 v25, v25
	v_exp_f32_e32 v26, v26
	v_exp_f32_e32 v27, v27
	v_exp_f32_e32 v28, v28
	v_exp_f32_e32 v29, v29
	v_exp_f32_e32 v30, v30
	v_exp_f32_e32 v31, v31
	v_pk_add_f32 v[24:25], v[24:25], 1.0 op_sel_hi:[1,0]
	v_pk_add_f32 v[26:27], v[26:27], 1.0 op_sel_hi:[1,0]
	v_pk_add_f32 v[28:29], v[28:29], 1.0 op_sel_hi:[1,0]
	v_pk_add_f32 v[30:31], v[30:31], 1.0 op_sel_hi:[1,0]
	v_rcp_f32_e32 v24, v24
	v_rcp_f32_e32 v25, v25
	v_rcp_f32_e32 v26, v26
	v_rcp_f32_e32 v27, v27
	v_rcp_f32_e32 v28, v28
	v_rcp_f32_e32 v29, v29
	v_rcp_f32_e32 v30, v30
	v_rcp_f32_e32 v31, v31
	v_pk_fma_f32 v[24:25], v[24:25], v[14:15], 0.5 op_sel_hi:[1,0,0]
	v_pk_fma_f32 v[26:27], v[26:27], v[14:15], 0.5 op_sel_hi:[1,0,0]
	v_pk_fma_f32 v[28:29], v[28:29], v[14:15], 0.5 op_sel_hi:[1,0,0]
	v_pk_fma_f32 v[30:31], v[30:31], v[14:15], 0.5 op_sel_hi:[1,0,0]
	v_med3_f32 v24, v24, 1.0, v232
	v_med3_f32 v25, v25, 1.0, v232
	v_med3_f32 v26, v26, 1.0, v232
	v_med3_f32 v27, v27, 1.0, v232
	v_med3_f32 v28, v28, 1.0, v232
	v_med3_f32 v29, v29, 1.0, v232
	v_med3_f32 v30, v30, 1.0, v232
	v_med3_f32 v31, v31, 1.0, v232
	v_cvt_u32_f32_e32 v24, v24
	v_cvt_u32_f32_e32 v25, v25
	v_cvt_u32_f32_sdwa v26, v26 dst_sel:WORD_1 dst_unused:UNUSED_PAD src0_sel:DWORD
	v_cvt_u32_f32_sdwa v27, v27 dst_sel:BYTE_3 dst_unused:UNUSED_PAD src0_sel:DWORD
	v_cvt_u32_f32_e32 v28, v28
	v_cvt_u32_f32_e32 v29, v29
	v_cvt_u32_f32_sdwa v30, v30 dst_sel:WORD_1 dst_unused:UNUSED_PAD src0_sel:DWORD
	v_cvt_u32_f32_sdwa v31, v31 dst_sel:BYTE_3 dst_unused:UNUSED_PAD src0_sel:DWORD
	v_lshl_or_b32 v24, v25, 8, v24
	v_lshl_or_b32 v28, v29, 8, v28
	v_or3_b32 v24, v24, v26, v27
	v_or3_b32 v25, v28, v30, v31
	global_store_dwordx2 v[8:9], v[24:25], off offset:128
	v_add_u32_e32 v8, 0xa0, v4
	v_mad_i64_i32 v[8:9], s[50:51], v8, s33, v[2:3]
	v_lshl_add_u64 v[8:9], v[8:9], 0, s[48:49]
	v_lshl_add_u64 v[8:9], v[8:9], 0, v[192:193]
	v_pk_mul_f32 v[16:17], v[206:207], v[64:65] op_sel_hi:[0,1]
	v_pk_mul_f32 v[18:19], v[206:207], v[66:67] op_sel_hi:[0,1]
	v_pk_mul_f32 v[20:21], v[206:207], v[60:61] op_sel_hi:[0,1]
	v_pk_mul_f32 v[22:23], v[206:207], v[62:63] op_sel_hi:[0,1]
	v_med3_f32 v16, v16, s96, v231
	v_med3_f32 v17, v17, s96, v231
	v_med3_f32 v18, v18, s96, v231
	v_med3_f32 v19, v19, s96, v231
	v_med3_f32 v20, v20, s96, v231
	v_med3_f32 v21, v21, s96, v231
	v_med3_f32 v22, v22, s96, v231
	v_med3_f32 v23, v23, s96, v231
	v_pk_mul_f32 v[16:17], v[16:17], s[98:99]
	v_pk_mul_f32 v[18:19], v[18:19], s[98:99]
	v_pk_mul_f32 v[20:21], v[20:21], s[98:99]
	v_pk_mul_f32 v[22:23], v[22:23], s[98:99]
	v_exp_f32_e32 v16, v16
	v_exp_f32_e32 v17, v17
	v_exp_f32_e32 v18, v18
	v_exp_f32_e32 v19, v19
	v_exp_f32_e32 v20, v20
	v_exp_f32_e32 v21, v21
	v_exp_f32_e32 v22, v22
	v_exp_f32_e32 v23, v23
	v_pk_add_f32 v[16:17], v[16:17], 1.0 op_sel_hi:[1,0]
	v_pk_add_f32 v[18:19], v[18:19], 1.0 op_sel_hi:[1,0]
	v_pk_add_f32 v[20:21], v[20:21], 1.0 op_sel_hi:[1,0]
	v_pk_add_f32 v[22:23], v[22:23], 1.0 op_sel_hi:[1,0]
	v_rcp_f32_e32 v16, v16
	v_rcp_f32_e32 v17, v17
	v_rcp_f32_e32 v18, v18
	v_rcp_f32_e32 v19, v19
	v_rcp_f32_e32 v20, v20
	v_rcp_f32_e32 v21, v21
	v_rcp_f32_e32 v22, v22
	v_rcp_f32_e32 v23, v23
	v_pk_fma_f32 v[16:17], v[16:17], v[14:15], 0.5 op_sel_hi:[1,0,0]
	v_pk_fma_f32 v[18:19], v[18:19], v[14:15], 0.5 op_sel_hi:[1,0,0]
	v_pk_fma_f32 v[20:21], v[20:21], v[14:15], 0.5 op_sel_hi:[1,0,0]
	v_pk_fma_f32 v[22:23], v[22:23], v[14:15], 0.5 op_sel_hi:[1,0,0]
	v_med3_f32 v16, v16, 1.0, v232
	v_med3_f32 v17, v17, 1.0, v232
	v_med3_f32 v18, v18, 1.0, v232
	v_med3_f32 v19, v19, 1.0, v232
	v_med3_f32 v20, v20, 1.0, v232
	v_med3_f32 v21, v21, 1.0, v232
	v_med3_f32 v22, v22, 1.0, v232
	v_med3_f32 v23, v23, 1.0, v232
	v_cvt_u32_f32_e32 v16, v16
	v_cvt_u32_f32_e32 v17, v17
	v_cvt_u32_f32_sdwa v18, v18 dst_sel:WORD_1 dst_unused:UNUSED_PAD src0_sel:DWORD
	v_cvt_u32_f32_sdwa v19, v19 dst_sel:BYTE_3 dst_unused:UNUSED_PAD src0_sel:DWORD
	v_cvt_u32_f32_e32 v20, v20
	v_cvt_u32_f32_e32 v21, v21
	v_cvt_u32_f32_sdwa v22, v22 dst_sel:WORD_1 dst_unused:UNUSED_PAD src0_sel:DWORD
	v_cvt_u32_f32_sdwa v23, v23 dst_sel:BYTE_3 dst_unused:UNUSED_PAD src0_sel:DWORD
	v_lshl_or_b32 v16, v17, 8, v16
	v_lshl_or_b32 v20, v21, 8, v20
	v_or3_b32 v16, v16, v18, v19
	v_or3_b32 v17, v20, v22, v23
	global_store_dwordx2 v[8:9], v[16:17], off
	v_pk_mul_f32 v[24:25], v[206:207], v[56:57] op_sel_hi:[0,1]
	v_pk_mul_f32 v[26:27], v[206:207], v[58:59] op_sel_hi:[0,1]
	v_pk_mul_f32 v[28:29], v[206:207], v[52:53] op_sel_hi:[0,1]
	v_pk_mul_f32 v[30:31], v[206:207], v[54:55] op_sel_hi:[0,1]
	v_med3_f32 v24, v24, s96, v231
	v_med3_f32 v25, v25, s96, v231
	v_med3_f32 v26, v26, s96, v231
	v_med3_f32 v27, v27, s96, v231
	v_med3_f32 v28, v28, s96, v231
	v_med3_f32 v29, v29, s96, v231
	v_med3_f32 v30, v30, s96, v231
	v_med3_f32 v31, v31, s96, v231
	v_pk_mul_f32 v[24:25], v[24:25], s[98:99]
	v_pk_mul_f32 v[26:27], v[26:27], s[98:99]
	v_pk_mul_f32 v[28:29], v[28:29], s[98:99]
	v_pk_mul_f32 v[30:31], v[30:31], s[98:99]
	v_exp_f32_e32 v24, v24
	v_exp_f32_e32 v25, v25
	v_exp_f32_e32 v26, v26
	v_exp_f32_e32 v27, v27
	v_exp_f32_e32 v28, v28
	v_exp_f32_e32 v29, v29
	v_exp_f32_e32 v30, v30
	v_exp_f32_e32 v31, v31
	v_pk_add_f32 v[24:25], v[24:25], 1.0 op_sel_hi:[1,0]
	v_pk_add_f32 v[26:27], v[26:27], 1.0 op_sel_hi:[1,0]
	v_pk_add_f32 v[28:29], v[28:29], 1.0 op_sel_hi:[1,0]
	v_pk_add_f32 v[30:31], v[30:31], 1.0 op_sel_hi:[1,0]
	v_rcp_f32_e32 v24, v24
	v_rcp_f32_e32 v25, v25
	v_rcp_f32_e32 v26, v26
	v_rcp_f32_e32 v27, v27
; #define PG8_BAR __builtin_amdgcn_s_barrier()
;     __device__ __forceinline__ void operator()(const f32x4 (&acc)[2][2][4][2], const Unit& u, int wr, int wc, int fr, int fq) const {
;     ...
;                 for (int bj = 0; bj < 2; ++bj) { const f32x4 v0 = acc[ai][bj][m][0] * sc, v1 = acc[ai][bj][m][1] * sc; unsigned q[8];
; #pragma unroll
;                     for (int j = 0; j < 4; ++j) { const float s0 = 255.0f * __builtin_amdgcn_rcpf(1.0f + __builtin_amdgcn_exp2f(-1.44269504089f * __builtin_amdgcn_fmed3f(v0[j], -30.f, 30.f))) + 0.5f,
;                                                               s1 = 255.0f * __builtin_amdgcn_rcpf(1.0f + __builtin_amdgcn_exp2f(-1.44269504089f * __builtin_amdgcn_fmed3f(v1[j], -30.f, 30.f))) + 0.5f;
;                         q[j] = (unsigned)__builtin_amdgcn_fmed3f(s0, 1.0f, 255.0f); q[4 + j] = (unsigned)__builtin_amdgcn_fmed3f(s1, 1.0f, 255.0f); }
;                     u32x2 w; w.x = q[0] | (q[1] << 8) | (q[2] << 16) | (q[3] << 24); w.y = q[4] | (q[5] << 8) | (q[6] << 16) | (q[7] << 24);
;                     *(u32x2*)(Q + row * 6144 + u.pn * BM + colt + bj * HALF) = w; } }
;     ...
;         if (!has_next) break;
;         if (!Epi::SEGMENTED || cur.seg == 2)
; #pragma unroll
;         for (int a = 0; a < 2; ++a)
; #pragma unroll
;             for (int b = 0; b < 2; ++b)
; #pragma unroll
;                 for (int m = 0; m < 4; ++m)
; #pragma unroll
;                     for (int n = 0; n < 2; ++n) acc[a][b][m][n] = (f32x4){0.f, 0.f, 0.f, 0.f};
;         cur = nxt; cA = nA; cB = nB; ++ui;
;         if constexpr (ALIGN_EPI) { if (wr == 1) PG8_BAR; }
	v_rcp_f32_e32 v28, v28
	v_rcp_f32_e32 v29, v29
	v_rcp_f32_e32 v30, v30
	v_rcp_f32_e32 v31, v31
	v_pk_fma_f32 v[24:25], v[24:25], v[14:15], 0.5 op_sel_hi:[1,0,0]
	v_pk_fma_f32 v[26:27], v[26:27], v[14:15], 0.5 op_sel_hi:[1,0,0]
	v_pk_fma_f32 v[28:29], v[28:29], v[14:15], 0.5 op_sel_hi:[1,0,0]
	v_pk_fma_f32 v[30:31], v[30:31], v[14:15], 0.5 op_sel_hi:[1,0,0]
	v_med3_f32 v24, v24, 1.0, v232
	v_med3_f32 v25, v25, 1.0, v232
	v_med3_f32 v26, v26, 1.0, v232
	v_med3_f32 v27, v27, 1.0, v232
	v_med3_f32 v28, v28, 1.0, v232
	v_med3_f32 v29, v29, 1.0, v232
	v_med3_f32 v30, v30, 1.0, v232
	v_med3_f32 v31, v31, 1.0, v232
	v_cvt_u32_f32_e32 v24, v24
	v_cvt_u32_f32_e32 v25, v25
	v_cvt_u32_f32_sdwa v26, v26 dst_sel:WORD_1 dst_unused:UNUSED_PAD src0_sel:DWORD
	v_cvt_u32_f32_sdwa v27, v27 dst_sel:BYTE_3 dst_unused:UNUSED_PAD src0_sel:DWORD
	v_cvt_u32_f32_e32 v28, v28
	v_cvt_u32_f32_e32 v29, v29
	v_cvt_u32_f32_sdwa v30, v30 dst_sel:WORD_1 dst_unused:UNUSED_PAD src0_sel:DWORD
	v_cvt_u32_f32_sdwa v31, v31 dst_sel:BYTE_3 dst_unused:UNUSED_PAD src0_sel:DWORD
	v_lshl_or_b32 v24, v25, 8, v24
	v_lshl_or_b32 v28, v29, 8, v28
	v_or3_b32 v24, v24, v26, v27
	v_or3_b32 v25, v28, v30, v31
	global_store_dwordx2 v[8:9], v[24:25], off offset:128
	v_add_u32_e32 v6, 0xb0, v4
	v_mad_i64_i32 v[2:3], s[50:51], v6, s33, v[2:3]
	v_lshl_add_u64 v[2:3], v[2:3], 0, s[48:49]
	v_lshl_add_u64 v[2:3], v[2:3], 0, v[192:193]
	v_pk_mul_f32 v[16:17], v[206:207], v[48:49] op_sel_hi:[0,1]
	v_pk_mul_f32 v[18:19], v[206:207], v[50:51] op_sel_hi:[0,1]
	v_pk_mul_f32 v[20:21], v[206:207], v[44:45] op_sel_hi:[0,1]
	v_pk_mul_f32 v[22:23], v[206:207], v[46:47] op_sel_hi:[0,1]
	v_med3_f32 v16, v16, s96, v231
	v_med3_f32 v17, v17, s96, v231
	v_med3_f32 v18, v18, s96, v231
	v_med3_f32 v19, v19, s96, v231
	v_med3_f32 v20, v20, s96, v231
	v_med3_f32 v21, v21, s96, v231
	v_med3_f32 v22, v22, s96, v231
	v_med3_f32 v23, v23, s96, v231
	v_pk_mul_f32 v[16:17], v[16:17], s[98:99]
	v_pk_mul_f32 v[18:19], v[18:19], s[98:99]
	v_pk_mul_f32 v[20:21], v[20:21], s[98:99]
	v_pk_mul_f32 v[22:23], v[22:23], s[98:99]
	v_exp_f32_e32 v16, v16
	v_exp_f32_e32 v17, v17
	v_exp_f32_e32 v18, v18
	v_exp_f32_e32 v19, v19
	v_exp_f32_e32 v20, v20
	v_exp_f32_e32 v21, v21
	v_exp_f32_e32 v22, v22
	v_exp_f32_e32 v23, v23
	v_pk_add_f32 v[16:17], v[16:17], 1.0 op_sel_hi:[1,0]
	v_pk_add_f32 v[18:19], v[18:19], 1.0 op_sel_hi:[1,0]
	v_pk_add_f32 v[20:21], v[20:21], 1.0 op_sel_hi:[1,0]
	v_pk_add_f32 v[22:23], v[22:23], 1.0 op_sel_hi:[1,0]
	v_rcp_f32_e32 v16, v16
	v_rcp_f32_e32 v17, v17
	v_rcp_f32_e32 v18, v18
	v_rcp_f32_e32 v19, v19
	v_rcp_f32_e32 v20, v20
	v_rcp_f32_e32 v21, v21
	v_rcp_f32_e32 v22, v22
	v_rcp_f32_e32 v23, v23
	v_pk_fma_f32 v[16:17], v[16:17], v[14:15], 0.5 op_sel_hi:[1,0,0]
	v_pk_fma_f32 v[18:19], v[18:19], v[14:15], 0.5 op_sel_hi:[1,0,0]
	v_pk_fma_f32 v[20:21], v[20:21], v[14:15], 0.5 op_sel_hi:[1,0,0]
	v_pk_fma_f32 v[22:23], v[22:23], v[14:15], 0.5 op_sel_hi:[1,0,0]
	v_med3_f32 v16, v16, 1.0, v232
	v_med3_f32 v17, v17, 1.0, v232
	v_med3_f32 v18, v18, 1.0, v232
	v_med3_f32 v19, v19, 1.0, v232
	v_med3_f32 v20, v20, 1.0, v232
	v_med3_f32 v21, v21, 1.0, v232
	v_med3_f32 v22, v22, 1.0, v232
	v_med3_f32 v23, v23, 1.0, v232
	v_cvt_u32_f32_e32 v16, v16
	v_cvt_u32_f32_e32 v17, v17
	v_cvt_u32_f32_sdwa v18, v18 dst_sel:WORD_1 dst_unused:UNUSED_PAD src0_sel:DWORD
	v_cvt_u32_f32_sdwa v19, v19 dst_sel:BYTE_3 dst_unused:UNUSED_PAD src0_sel:DWORD
	v_cvt_u32_f32_e32 v20, v20
	v_cvt_u32_f32_e32 v21, v21
	v_cvt_u32_f32_sdwa v22, v22 dst_sel:WORD_1 dst_unused:UNUSED_PAD src0_sel:DWORD
	v_cvt_u32_f32_sdwa v23, v23 dst_sel:BYTE_3 dst_unused:UNUSED_PAD src0_sel:DWORD
	v_lshl_or_b32 v16, v17, 8, v16
	v_lshl_or_b32 v20, v21, 8, v20
	v_or3_b32 v16, v16, v18, v19
	v_or3_b32 v17, v20, v22, v23
	global_store_dwordx2 v[2:3], v[16:17], off
	s_andn2_b64 vcc, exec, s[38:39]
	s_mov_b64 s[38:39], -1
	s_movk_i32 s71, 0x6ff
	v_pk_mul_f32 v[24:25], v[206:207], v[40:41] op_sel_hi:[0,1]
	v_pk_mul_f32 v[26:27], v[206:207], v[42:43] op_sel_hi:[0,1]
	v_pk_mul_f32 v[28:29], v[206:207], v[36:37] op_sel_hi:[0,1]
	v_pk_mul_f32 v[30:31], v[206:207], v[38:39] op_sel_hi:[0,1]
	v_med3_f32 v24, v24, s96, v231
	v_med3_f32 v25, v25, s96, v231
	v_med3_f32 v26, v26, s96, v231
	v_med3_f32 v27, v27, s96, v231
	v_med3_f32 v28, v28, s96, v231
	v_med3_f32 v29, v29, s96, v231
	v_med3_f32 v30, v30, s96, v231
	v_med3_f32 v31, v31, s96, v231
	v_pk_mul_f32 v[24:25], v[24:25], s[98:99]
	v_pk_mul_f32 v[26:27], v[26:27], s[98:99]
	v_pk_mul_f32 v[28:29], v[28:29], s[98:99]
	v_pk_mul_f32 v[30:31], v[30:31], s[98:99]
	v_exp_f32_e32 v24, v24
	v_exp_f32_e32 v25, v25
	v_exp_f32_e32 v26, v26
	v_exp_f32_e32 v27, v27
	v_exp_f32_e32 v28, v28
	v_exp_f32_e32 v29, v29
	v_exp_f32_e32 v30, v30
	v_exp_f32_e32 v31, v31
	v_pk_add_f32 v[24:25], v[24:25], 1.0 op_sel_hi:[1,0]
	v_pk_add_f32 v[26:27], v[26:27], 1.0 op_sel_hi:[1,0]
	v_pk_add_f32 v[28:29], v[28:29], 1.0 op_sel_hi:[1,0]
	v_pk_add_f32 v[30:31], v[30:31], 1.0 op_sel_hi:[1,0]
	v_rcp_f32_e32 v24, v24
	v_rcp_f32_e32 v25, v25
	v_rcp_f32_e32 v26, v26
	v_rcp_f32_e32 v27, v27
	v_rcp_f32_e32 v28, v28
	v_rcp_f32_e32 v29, v29
	v_rcp_f32_e32 v30, v30
	v_rcp_f32_e32 v31, v31
	v_pk_fma_f32 v[24:25], v[24:25], v[14:15], 0.5 op_sel_hi:[1,0,0]
	v_pk_fma_f32 v[26:27], v[26:27], v[14:15], 0.5 op_sel_hi:[1,0,0]
	v_pk_fma_f32 v[28:29], v[28:29], v[14:15], 0.5 op_sel_hi:[1,0,0]
	v_pk_fma_f32 v[30:31], v[30:31], v[14:15], 0.5 op_sel_hi:[1,0,0]
	v_med3_f32 v24, v24, 1.0, v232
	v_med3_f32 v25, v25, 1.0, v232
	v_med3_f32 v26, v26, 1.0, v232
	v_med3_f32 v27, v27, 1.0, v232
	v_med3_f32 v28, v28, 1.0, v232
	v_med3_f32 v29, v29, 1.0, v232
	v_med3_f32 v30, v30, 1.0, v232
	v_med3_f32 v31, v31, 1.0, v232
	v_cvt_u32_f32_e32 v24, v24
	v_cvt_u32_f32_e32 v25, v25
	v_cvt_u32_f32_sdwa v26, v26 dst_sel:WORD_1 dst_unused:UNUSED_PAD src0_sel:DWORD
	v_cvt_u32_f32_sdwa v27, v27 dst_sel:BYTE_3 dst_unused:UNUSED_PAD src0_sel:DWORD
	v_cvt_u32_f32_e32 v28, v28
	v_cvt_u32_f32_e32 v29, v29
	v_cvt_u32_f32_sdwa v30, v30 dst_sel:WORD_1 dst_unused:UNUSED_PAD src0_sel:DWORD
	v_cvt_u32_f32_sdwa v31, v31 dst_sel:BYTE_3 dst_unused:UNUSED_PAD src0_sel:DWORD
	v_lshl_or_b32 v24, v25, 8, v24
	v_lshl_or_b32 v28, v29, 8, v28
	v_or3_b32 v24, v24, v26, v27
	v_or3_b32 v25, v28, v30, v31
	global_store_dwordx2 v[2:3], v[24:25], off offset:128
	s_cbranch_vccnz .LBB0_1129
	s_andn2_b64 vcc, exec, s[18:19]
	s_cbranch_vccnz .LBB0_1128
	s_barrier
	s_branch .LBB0_1128
